# v67: P6 second-pass epilogues E3/E4 hand-written (d16_hi slot loads pipelined by row group, running offsets, packed cvt) replacing the transformed compiler code
# speedup vs baseline: 1.0093x; 1.0051x over previous
.LBB0_3373:
	s_waitcnt vmcnt(0)
	s_cmpk_lt_i32 s0, 0x4000
	s_cbranch_scc1 .Lp6y_e4_f
	v_readfirstlane_b32 s64, v208
	s_bitcmp1_b32 s64, 8
	s_cbranch_scc1 .Lp6y_e4_e
.Lp6y_e4_f:
	v_mov_b32_e32 v144, 0
	v_mov_b32_e32 v145, 0
	v_mov_b32_e32 v146, 0
	v_mov_b32_e32 v147, 0
	v_mov_b32_e32 v148, 0
	v_mov_b32_e32 v149, 0
	v_mov_b32_e32 v150, 0
	v_mov_b32_e32 v151, 0
	v_mov_b32_e32 v152, 0
	v_mov_b32_e32 v153, 0
	v_mov_b32_e32 v154, 0
	v_mov_b32_e32 v155, 0
	v_mov_b32_e32 v156, 0
	v_mov_b32_e32 v157, 0
	v_mov_b32_e32 v158, 0
	v_mov_b32_e32 v159, 0
	v_mov_b32_e32 v160, 0
	v_mov_b32_e32 v161, 0
	v_mov_b32_e32 v162, 0
	v_mov_b32_e32 v163, 0
	v_mov_b32_e32 v164, 0
	v_mov_b32_e32 v165, 0
	v_mov_b32_e32 v166, 0
	v_mov_b32_e32 v167, 0
	v_mov_b32_e32 v168, 0
	v_mov_b32_e32 v169, 0
	v_mov_b32_e32 v170, 0
	v_mov_b32_e32 v171, 0
	v_mov_b32_e32 v172, 0
	v_mov_b32_e32 v173, 0
	v_mov_b32_e32 v174, 0
	v_mov_b32_e32 v175, 0
	v_mov_b32_e32 v176, 0
	v_mov_b32_e32 v177, 0
	v_mov_b32_e32 v178, 0
	v_mov_b32_e32 v179, 0
	v_mov_b32_e32 v180, 0
	v_mov_b32_e32 v181, 0
	v_mov_b32_e32 v182, 0
	v_mov_b32_e32 v183, 0
	v_mov_b32_e32 v184, 0
	v_mov_b32_e32 v185, 0
	v_mov_b32_e32 v186, 0
	v_mov_b32_e32 v187, 0
	v_mov_b32_e32 v188, 0
	v_mov_b32_e32 v189, 0
	v_mov_b32_e32 v190, 0
	v_mov_b32_e32 v191, 0
	v_lshrrev_b32_e32 v229, 3, v208
	v_and_b32_e32 v229, 4, v229
	v_lshrrev_b32_e32 v227, 1, v208
	v_and_b32_e32 v227, 0x80, v227
	v_or_b32_e32 v227, v227, v229
	v_and_b32_e32 v228, 0xdf, v208
	v_or_b32_e32 v228, s6, v228
	v_add_u32_e32 v229, s0, v227
	v_lshlrev_b32_e32 v229, 11, v229
	v_lshl_add_u32 v225, v228, 1, v229
	v_mov_b32_e32 v226, v225
	global_load_short_d16_hi v144, v226, s[18:19]
	global_load_short_d16_hi v152, v226, s[62:63]
	global_load_short_d16_hi v145, v226, s[18:19] offset:64
	global_load_short_d16_hi v153, v226, s[62:63] offset:64
	v_add_u32_e32 v226, 0x800, v226
	global_load_short_d16_hi v146, v226, s[18:19]
	global_load_short_d16_hi v154, v226, s[62:63]
	global_load_short_d16_hi v147, v226, s[18:19] offset:64
	global_load_short_d16_hi v155, v226, s[62:63] offset:64
	v_add_u32_e32 v226, 0x800, v226
	global_load_short_d16_hi v148, v226, s[18:19]
	global_load_short_d16_hi v156, v226, s[62:63]
	global_load_short_d16_hi v149, v226, s[18:19] offset:64
	global_load_short_d16_hi v157, v226, s[62:63] offset:64
	v_add_u32_e32 v226, 0x800, v226
	global_load_short_d16_hi v150, v226, s[18:19]
	global_load_short_d16_hi v158, v226, s[62:63]
	global_load_short_d16_hi v151, v226, s[18:19] offset:64
	global_load_short_d16_hi v159, v226, s[62:63] offset:64
	v_add_u32_e32 v226, 0x2800, v226
	global_load_short_d16_hi v160, v226, s[18:19]
	global_load_short_d16_hi v168, v226, s[62:63]
	global_load_short_d16_hi v161, v226, s[18:19] offset:64
	global_load_short_d16_hi v169, v226, s[62:63] offset:64
	v_add_u32_e32 v226, 0x800, v226
	global_load_short_d16_hi v162, v226, s[18:19]
	global_load_short_d16_hi v170, v226, s[62:63]
	global_load_short_d16_hi v163, v226, s[18:19] offset:64
	global_load_short_d16_hi v171, v226, s[62:63] offset:64
	v_add_u32_e32 v226, 0x800, v226
	global_load_short_d16_hi v164, v226, s[18:19]
	global_load_short_d16_hi v172, v226, s[62:63]
	global_load_short_d16_hi v165, v226, s[18:19] offset:64
	global_load_short_d16_hi v173, v226, s[62:63] offset:64
	v_add_u32_e32 v226, 0x800, v226
	global_load_short_d16_hi v166, v226, s[18:19]
	global_load_short_d16_hi v174, v226, s[62:63]
	global_load_short_d16_hi v167, v226, s[18:19] offset:64
	global_load_short_d16_hi v175, v226, s[62:63] offset:64
	v_add_u32_e32 v226, 0x2800, v226
	global_load_short_d16_hi v176, v226, s[18:19]
	global_load_short_d16_hi v184, v226, s[62:63]
	global_load_short_d16_hi v177, v226, s[18:19] offset:64
	global_load_short_d16_hi v185, v226, s[62:63] offset:64
	v_add_u32_e32 v226, 0x800, v226
	global_load_short_d16_hi v178, v226, s[18:19]
	global_load_short_d16_hi v186, v226, s[62:63]
	global_load_short_d16_hi v179, v226, s[18:19] offset:64
	global_load_short_d16_hi v187, v226, s[62:63] offset:64
	v_add_u32_e32 v226, 0x800, v226
	global_load_short_d16_hi v180, v226, s[18:19]
	global_load_short_d16_hi v188, v226, s[62:63]
	global_load_short_d16_hi v181, v226, s[18:19] offset:64
	global_load_short_d16_hi v189, v226, s[62:63] offset:64
	v_add_u32_e32 v226, 0x800, v226
	global_load_short_d16_hi v182, v226, s[18:19]
	global_load_short_d16_hi v190, v226, s[62:63]
	global_load_short_d16_hi v183, v226, s[18:19] offset:64
	global_load_short_d16_hi v191, v226, s[62:63] offset:64
	v_add_u32_e32 v226, 0x2800, v226
	s_waitcnt vmcnt(32)
	v_fma_f32 v209, v128, v152, v144
	v_fma_f32 v210, v112, v153, v145
	v_fma_f32 v211, v129, v154, v146
	v_fma_f32 v212, v113, v155, v147
	v_fma_f32 v213, v130, v156, v148
	v_fma_f32 v214, v114, v157, v149
	v_fma_f32 v215, v131, v158, v150
	v_fma_f32 v216, v115, v159, v151
	v_cvt_pk_bf16_f32 v217, v209, v211
	v_cvt_pk_bf16_f32 v218, v213, v215
	v_cvt_pk_bf16_f32 v219, v210, v212
	v_cvt_pk_bf16_f32 v220, v214, v216
	global_store_short v225, v217, s[18:19]
	global_store_short v225, v219, s[18:19] offset:64
	v_add_u32_e32 v225, 0x800, v225
	global_store_short_d16_hi v225, v217, s[18:19]
	global_store_short_d16_hi v225, v219, s[18:19] offset:64
	v_add_u32_e32 v225, 0x800, v225
	global_store_short v225, v218, s[18:19]
	global_store_short v225, v220, s[18:19] offset:64
	v_add_u32_e32 v225, 0x800, v225
	global_store_short_d16_hi v225, v218, s[18:19]
	global_store_short_d16_hi v225, v220, s[18:19] offset:64
	v_add_u32_e32 v225, 0x2800, v225
	global_load_short_d16_hi v144, v226, s[18:19]
	global_load_short_d16_hi v152, v226, s[62:63]
	global_load_short_d16_hi v145, v226, s[18:19] offset:64
	global_load_short_d16_hi v153, v226, s[62:63] offset:64
	v_add_u32_e32 v226, 0x800, v226
	global_load_short_d16_hi v146, v226, s[18:19]
	global_load_short_d16_hi v154, v226, s[62:63]
	global_load_short_d16_hi v147, v226, s[18:19] offset:64
	global_load_short_d16_hi v155, v226, s[62:63] offset:64
	v_add_u32_e32 v226, 0x800, v226
	global_load_short_d16_hi v148, v226, s[18:19]
	global_load_short_d16_hi v156, v226, s[62:63]
	global_load_short_d16_hi v149, v226, s[18:19] offset:64
	global_load_short_d16_hi v157, v226, s[62:63] offset:64
	v_add_u32_e32 v226, 0x800, v226
	global_load_short_d16_hi v150, v226, s[18:19]
	global_load_short_d16_hi v158, v226, s[62:63]
	global_load_short_d16_hi v151, v226, s[18:19] offset:64
	global_load_short_d16_hi v159, v226, s[62:63] offset:64
	v_add_u32_e32 v226, 0x2800, v226
	s_waitcnt vmcnt(40)
	v_fma_f32 v209, v132, v168, v160
	v_fma_f32 v210, v116, v169, v161
	v_fma_f32 v211, v133, v170, v162
	v_fma_f32 v212, v117, v171, v163
	v_fma_f32 v213, v134, v172, v164
	v_fma_f32 v214, v118, v173, v165
	v_fma_f32 v215, v135, v174, v166
	v_fma_f32 v216, v119, v175, v167
	v_cvt_pk_bf16_f32 v221, v209, v211
	v_cvt_pk_bf16_f32 v222, v213, v215
	v_cvt_pk_bf16_f32 v223, v210, v212
	v_cvt_pk_bf16_f32 v224, v214, v216
	global_store_short v225, v221, s[18:19]
	global_store_short v225, v223, s[18:19] offset:64
	v_add_u32_e32 v225, 0x800, v225
	global_store_short_d16_hi v225, v221, s[18:19]
	global_store_short_d16_hi v225, v223, s[18:19] offset:64
	v_add_u32_e32 v225, 0x800, v225
	global_store_short v225, v222, s[18:19]
	global_store_short v225, v224, s[18:19] offset:64
	v_add_u32_e32 v225, 0x800, v225
	global_store_short_d16_hi v225, v222, s[18:19]
	global_store_short_d16_hi v225, v224, s[18:19] offset:64
	v_add_u32_e32 v225, 0x2800, v225
	global_load_short_d16_hi v160, v226, s[18:19]
	global_load_short_d16_hi v168, v226, s[62:63]
	global_load_short_d16_hi v161, v226, s[18:19] offset:64
	global_load_short_d16_hi v169, v226, s[62:63] offset:64
	v_add_u32_e32 v226, 0x800, v226
	global_load_short_d16_hi v162, v226, s[18:19]
	global_load_short_d16_hi v170, v226, s[62:63]
	global_load_short_d16_hi v163, v226, s[18:19] offset:64
	global_load_short_d16_hi v171, v226, s[62:63] offset:64
	v_add_u32_e32 v226, 0x800, v226
	s_waitcnt vmcnt(40)
	global_load_short_d16_hi v164, v226, s[18:19]
	global_load_short_d16_hi v172, v226, s[62:63]
	global_load_short_d16_hi v165, v226, s[18:19] offset:64
	global_load_short_d16_hi v173, v226, s[62:63] offset:64
	v_add_u32_e32 v226, 0x800, v226
	global_load_short_d16_hi v166, v226, s[18:19]
	global_load_short_d16_hi v174, v226, s[62:63]
	global_load_short_d16_hi v167, v226, s[18:19] offset:64
	global_load_short_d16_hi v175, v226, s[62:63] offset:64
	v_add_u32_e32 v226, 0x2800, v226
	v_fma_f32 v209, v136, v184, v176
	v_fma_f32 v210, v120, v185, v177
	v_fma_f32 v211, v137, v186, v178
	v_fma_f32 v212, v121, v187, v179
	v_fma_f32 v213, v138, v188, v180
	v_fma_f32 v214, v122, v189, v181
	v_fma_f32 v215, v139, v190, v182
	v_fma_f32 v216, v123, v191, v183
	v_cvt_pk_bf16_f32 v217, v209, v211
	v_cvt_pk_bf16_f32 v218, v213, v215
	v_cvt_pk_bf16_f32 v219, v210, v212
	v_cvt_pk_bf16_f32 v220, v214, v216
	global_store_short v225, v217, s[18:19]
	global_store_short v225, v219, s[18:19] offset:64
	v_add_u32_e32 v225, 0x800, v225
	global_store_short_d16_hi v225, v217, s[18:19]
	global_store_short_d16_hi v225, v219, s[18:19] offset:64
	v_add_u32_e32 v225, 0x800, v225
	global_store_short v225, v218, s[18:19]
	global_store_short v225, v220, s[18:19] offset:64
	v_add_u32_e32 v225, 0x800, v225
	global_store_short_d16_hi v225, v218, s[18:19]
	global_store_short_d16_hi v225, v220, s[18:19] offset:64
	v_add_u32_e32 v225, 0x2800, v225
	s_waitcnt vmcnt(40)
	global_load_short_d16_hi v176, v226, s[18:19]
	global_load_short_d16_hi v184, v226, s[62:63]
	global_load_short_d16_hi v177, v226, s[18:19] offset:64
	global_load_short_d16_hi v185, v226, s[62:63] offset:64
	v_add_u32_e32 v226, 0x800, v226
	global_load_short_d16_hi v178, v226, s[18:19]
	global_load_short_d16_hi v186, v226, s[62:63]
	global_load_short_d16_hi v179, v226, s[18:19] offset:64
	global_load_short_d16_hi v187, v226, s[62:63] offset:64
	v_add_u32_e32 v226, 0x800, v226
	global_load_short_d16_hi v180, v226, s[18:19]
	global_load_short_d16_hi v188, v226, s[62:63]
	global_load_short_d16_hi v181, v226, s[18:19] offset:64
	global_load_short_d16_hi v189, v226, s[62:63] offset:64
	v_add_u32_e32 v226, 0x800, v226
	global_load_short_d16_hi v182, v226, s[18:19]
	global_load_short_d16_hi v190, v226, s[62:63]
	global_load_short_d16_hi v183, v226, s[18:19] offset:64
	global_load_short_d16_hi v191, v226, s[62:63] offset:64
	v_add_u32_e32 v226, 0x2800, v226
	s_waitcnt vmcnt(48)
	v_fma_f32 v209, v140, v152, v144
	v_fma_f32 v210, v124, v153, v145
	v_fma_f32 v211, v141, v154, v146
	v_fma_f32 v212, v125, v155, v147
	v_fma_f32 v213, v142, v156, v148
	v_fma_f32 v214, v126, v157, v149
	v_fma_f32 v215, v143, v158, v150
	v_fma_f32 v216, v127, v159, v151
	v_cvt_pk_bf16_f32 v221, v209, v211
	v_cvt_pk_bf16_f32 v222, v213, v215
	v_cvt_pk_bf16_f32 v223, v210, v212
	v_cvt_pk_bf16_f32 v224, v214, v216
	global_store_short v225, v221, s[18:19]
	global_store_short v225, v223, s[18:19] offset:64
	v_add_u32_e32 v225, 0x800, v225
	global_store_short_d16_hi v225, v221, s[18:19]
	global_store_short_d16_hi v225, v223, s[18:19] offset:64
	v_add_u32_e32 v225, 0x800, v225
	global_store_short v225, v222, s[18:19]
	global_store_short v225, v224, s[18:19] offset:64
	v_add_u32_e32 v225, 0x800, v225
	global_store_short_d16_hi v225, v222, s[18:19]
	global_store_short_d16_hi v225, v224, s[18:19] offset:64
	v_add_u32_e32 v225, 0x2800, v225
	s_waitcnt vmcnt(40)
	global_load_short_d16_hi v144, v226, s[18:19]
	global_load_short_d16_hi v152, v226, s[62:63]
	global_load_short_d16_hi v145, v226, s[18:19] offset:64
	global_load_short_d16_hi v153, v226, s[62:63] offset:64
	v_add_u32_e32 v226, 0x800, v226
	global_load_short_d16_hi v146, v226, s[18:19]
	global_load_short_d16_hi v154, v226, s[62:63]
	global_load_short_d16_hi v147, v226, s[18:19] offset:64
	global_load_short_d16_hi v155, v226, s[62:63] offset:64
	v_add_u32_e32 v226, 0x800, v226
	global_load_short_d16_hi v148, v226, s[18:19]
	global_load_short_d16_hi v156, v226, s[62:63]
	global_load_short_d16_hi v149, v226, s[18:19] offset:64
	global_load_short_d16_hi v157, v226, s[62:63] offset:64
	v_add_u32_e32 v226, 0x800, v226
	global_load_short_d16_hi v150, v226, s[18:19]
	global_load_short_d16_hi v158, v226, s[62:63]
	global_load_short_d16_hi v151, v226, s[18:19] offset:64
	global_load_short_d16_hi v159, v226, s[62:63] offset:64
	v_add_u32_e32 v226, 0x2800, v226
	s_waitcnt vmcnt(48)
	v_fma_f32 v209, v96, v168, v160
	v_fma_f32 v210, v80, v169, v161
	v_fma_f32 v211, v97, v170, v162
	v_fma_f32 v212, v81, v171, v163
	v_fma_f32 v213, v98, v172, v164
	v_fma_f32 v214, v82, v173, v165
	v_fma_f32 v215, v99, v174, v166
	v_fma_f32 v216, v83, v175, v167
	v_cvt_pk_bf16_f32 v217, v209, v211
	v_cvt_pk_bf16_f32 v218, v213, v215
	v_cvt_pk_bf16_f32 v219, v210, v212
	v_cvt_pk_bf16_f32 v220, v214, v216
	global_store_short v225, v217, s[18:19]
	global_store_short v225, v219, s[18:19] offset:64
	v_add_u32_e32 v225, 0x800, v225
	global_store_short_d16_hi v225, v217, s[18:19]
	global_store_short_d16_hi v225, v219, s[18:19] offset:64
	v_add_u32_e32 v225, 0x800, v225
	global_store_short v225, v218, s[18:19]
	global_store_short v225, v220, s[18:19] offset:64
	v_add_u32_e32 v225, 0x800, v225
	global_store_short_d16_hi v225, v218, s[18:19]
	global_store_short_d16_hi v225, v220, s[18:19] offset:64
	v_add_u32_e32 v225, 0x2800, v225
	s_waitcnt vmcnt(40)
	global_load_short_d16_hi v160, v226, s[18:19]
	global_load_short_d16_hi v168, v226, s[62:63]
	global_load_short_d16_hi v161, v226, s[18:19] offset:64
	global_load_short_d16_hi v169, v226, s[62:63] offset:64
	v_add_u32_e32 v226, 0x800, v226
	global_load_short_d16_hi v162, v226, s[18:19]
	global_load_short_d16_hi v170, v226, s[62:63]
	global_load_short_d16_hi v163, v226, s[18:19] offset:64
	global_load_short_d16_hi v171, v226, s[62:63] offset:64
	v_add_u32_e32 v226, 0x800, v226
	global_load_short_d16_hi v164, v226, s[18:19]
	global_load_short_d16_hi v172, v226, s[62:63]
	global_load_short_d16_hi v165, v226, s[18:19] offset:64
	global_load_short_d16_hi v173, v226, s[62:63] offset:64
	v_add_u32_e32 v226, 0x800, v226
	global_load_short_d16_hi v166, v226, s[18:19]
	global_load_short_d16_hi v174, v226, s[62:63]
	global_load_short_d16_hi v167, v226, s[18:19] offset:64
	global_load_short_d16_hi v175, v226, s[62:63] offset:64
	v_add_u32_e32 v226, 0x2800, v226
	s_waitcnt vmcnt(48)
	v_fma_f32 v209, v100, v184, v176
	v_fma_f32 v210, v84, v185, v177
	v_fma_f32 v211, v101, v186, v178
	v_fma_f32 v212, v85, v187, v179
	v_fma_f32 v213, v102, v188, v180
	v_fma_f32 v214, v86, v189, v181
	v_fma_f32 v215, v103, v190, v182
	v_fma_f32 v216, v87, v191, v183
	v_cvt_pk_bf16_f32 v221, v209, v211
	v_cvt_pk_bf16_f32 v222, v213, v215
	v_cvt_pk_bf16_f32 v223, v210, v212
	v_cvt_pk_bf16_f32 v224, v214, v216
	global_store_short v225, v221, s[18:19]
	global_store_short v225, v223, s[18:19] offset:64
	v_add_u32_e32 v225, 0x800, v225
	global_store_short_d16_hi v225, v221, s[18:19]
	global_store_short_d16_hi v225, v223, s[18:19] offset:64
	v_add_u32_e32 v225, 0x800, v225
	global_store_short v225, v222, s[18:19]
	global_store_short v225, v224, s[18:19] offset:64
	v_add_u32_e32 v225, 0x800, v225
	global_store_short_d16_hi v225, v222, s[18:19]
	global_store_short_d16_hi v225, v224, s[18:19] offset:64
	v_add_u32_e32 v225, 0x2800, v225
	s_waitcnt vmcnt(40)
	global_load_short_d16_hi v176, v226, s[18:19]
	global_load_short_d16_hi v184, v226, s[62:63]
	global_load_short_d16_hi v177, v226, s[18:19] offset:64
	global_load_short_d16_hi v185, v226, s[62:63] offset:64
	v_add_u32_e32 v226, 0x800, v226
	global_load_short_d16_hi v178, v226, s[18:19]
	global_load_short_d16_hi v186, v226, s[62:63]
	global_load_short_d16_hi v179, v226, s[18:19] offset:64
	global_load_short_d16_hi v187, v226, s[62:63] offset:64
	v_add_u32_e32 v226, 0x800, v226
	global_load_short_d16_hi v180, v226, s[18:19]
	global_load_short_d16_hi v188, v226, s[62:63]
	global_load_short_d16_hi v181, v226, s[18:19] offset:64
	global_load_short_d16_hi v189, v226, s[62:63] offset:64
	v_add_u32_e32 v226, 0x800, v226
	global_load_short_d16_hi v182, v226, s[18:19]
	global_load_short_d16_hi v190, v226, s[62:63]
	global_load_short_d16_hi v183, v226, s[18:19] offset:64
	global_load_short_d16_hi v191, v226, s[62:63] offset:64
	v_add_u32_e32 v226, 0x2800, v226
	s_waitcnt vmcnt(48)
	v_fma_f32 v209, v104, v152, v144
	v_fma_f32 v210, v88, v153, v145
	v_fma_f32 v211, v105, v154, v146
	v_fma_f32 v212, v89, v155, v147
	v_fma_f32 v213, v106, v156, v148
	v_fma_f32 v214, v90, v157, v149
	v_fma_f32 v215, v107, v158, v150
	v_fma_f32 v216, v91, v159, v151
	v_cvt_pk_bf16_f32 v217, v209, v211
	v_cvt_pk_bf16_f32 v218, v213, v215
	v_cvt_pk_bf16_f32 v219, v210, v212
	v_cvt_pk_bf16_f32 v220, v214, v216
	global_store_short v225, v217, s[18:19]
	global_store_short v225, v219, s[18:19] offset:64
	v_add_u32_e32 v225, 0x800, v225
	global_store_short_d16_hi v225, v217, s[18:19]
	global_store_short_d16_hi v225, v219, s[18:19] offset:64
	v_add_u32_e32 v225, 0x800, v225
	global_store_short v225, v218, s[18:19]
	global_store_short v225, v220, s[18:19] offset:64
	v_add_u32_e32 v225, 0x800, v225
	global_store_short_d16_hi v225, v218, s[18:19]
	global_store_short_d16_hi v225, v220, s[18:19] offset:64
	v_add_u32_e32 v225, 0x2800, v225
	s_waitcnt vmcnt(40)
	global_load_short_d16_hi v144, v226, s[18:19]
	global_load_short_d16_hi v152, v226, s[62:63]
	global_load_short_d16_hi v145, v226, s[18:19] offset:64
	global_load_short_d16_hi v153, v226, s[62:63] offset:64
	v_add_u32_e32 v226, 0x800, v226
	global_load_short_d16_hi v146, v226, s[18:19]
	global_load_short_d16_hi v154, v226, s[62:63]
	global_load_short_d16_hi v147, v226, s[18:19] offset:64
	global_load_short_d16_hi v155, v226, s[62:63] offset:64
	v_add_u32_e32 v226, 0x800, v226
	global_load_short_d16_hi v148, v226, s[18:19]
	global_load_short_d16_hi v156, v226, s[62:63]
	global_load_short_d16_hi v149, v226, s[18:19] offset:64
	global_load_short_d16_hi v157, v226, s[62:63] offset:64
	v_add_u32_e32 v226, 0x800, v226
	global_load_short_d16_hi v150, v226, s[18:19]
	global_load_short_d16_hi v158, v226, s[62:63]
	global_load_short_d16_hi v151, v226, s[18:19] offset:64
	global_load_short_d16_hi v159, v226, s[62:63] offset:64
	v_add_u32_e32 v226, 0x2800, v226
	s_waitcnt vmcnt(48)
	v_fma_f32 v209, v108, v168, v160
	v_fma_f32 v210, v92, v169, v161
	v_fma_f32 v211, v109, v170, v162
	v_fma_f32 v212, v93, v171, v163
	v_fma_f32 v213, v110, v172, v164
	v_fma_f32 v214, v94, v173, v165
	v_fma_f32 v215, v111, v174, v166
	v_fma_f32 v216, v95, v175, v167
	v_cvt_pk_bf16_f32 v221, v209, v211
	v_cvt_pk_bf16_f32 v222, v213, v215
	v_cvt_pk_bf16_f32 v223, v210, v212
	v_cvt_pk_bf16_f32 v224, v214, v216
	global_store_short v225, v221, s[18:19]
	global_store_short v225, v223, s[18:19] offset:64
	v_add_u32_e32 v225, 0x800, v225
	global_store_short_d16_hi v225, v221, s[18:19]
	global_store_short_d16_hi v225, v223, s[18:19] offset:64
	v_add_u32_e32 v225, 0x800, v225
	global_store_short v225, v222, s[18:19]
	global_store_short v225, v224, s[18:19] offset:64
	v_add_u32_e32 v225, 0x800, v225
	global_store_short_d16_hi v225, v222, s[18:19]
	global_store_short_d16_hi v225, v224, s[18:19] offset:64
	v_add_u32_e32 v225, 0x2800, v225
	s_cmpk_lt_i32 s0, 0x4000
	s_cbranch_scc1 .Lp6y_e4_c
	s_waitcnt vmcnt(0)
	s_branch .Lp6y_e4_e
.Lp6y_e4_c:
	s_waitcnt vmcnt(40)
	global_load_short_d16_hi v160, v226, s[18:19]
	global_load_short_d16_hi v168, v226, s[62:63]
	global_load_short_d16_hi v161, v226, s[18:19] offset:64
	global_load_short_d16_hi v169, v226, s[62:63] offset:64
	v_add_u32_e32 v226, 0x800, v226
	global_load_short_d16_hi v162, v226, s[18:19]
	global_load_short_d16_hi v170, v226, s[62:63]
	global_load_short_d16_hi v163, v226, s[18:19] offset:64
	global_load_short_d16_hi v171, v226, s[62:63] offset:64
	v_add_u32_e32 v226, 0x800, v226
	global_load_short_d16_hi v164, v226, s[18:19]
	global_load_short_d16_hi v172, v226, s[62:63]
	global_load_short_d16_hi v165, v226, s[18:19] offset:64
	global_load_short_d16_hi v173, v226, s[62:63] offset:64
	v_add_u32_e32 v226, 0x800, v226
	global_load_short_d16_hi v166, v226, s[18:19]
	global_load_short_d16_hi v174, v226, s[62:63]
	global_load_short_d16_hi v167, v226, s[18:19] offset:64
	global_load_short_d16_hi v175, v226, s[62:63] offset:64
	v_add_u32_e32 v226, 0x2800, v226
	s_waitcnt vmcnt(48)
	v_fma_f32 v209, v64, v184, v176
	v_fma_f32 v210, v48, v185, v177
	v_fma_f32 v211, v65, v186, v178
	v_fma_f32 v212, v49, v187, v179
	v_fma_f32 v213, v66, v188, v180
	v_fma_f32 v214, v50, v189, v181
	v_fma_f32 v215, v67, v190, v182
	v_fma_f32 v216, v51, v191, v183
	v_cvt_pk_bf16_f32 v217, v209, v211
	v_cvt_pk_bf16_f32 v218, v213, v215
	v_cvt_pk_bf16_f32 v219, v210, v212
	v_cvt_pk_bf16_f32 v220, v214, v216
	global_store_short v225, v217, s[18:19]
	global_store_short v225, v219, s[18:19] offset:64
	v_add_u32_e32 v225, 0x800, v225
	global_store_short_d16_hi v225, v217, s[18:19]
	global_store_short_d16_hi v225, v219, s[18:19] offset:64
	v_add_u32_e32 v225, 0x800, v225
	global_store_short v225, v218, s[18:19]
	global_store_short v225, v220, s[18:19] offset:64
	v_add_u32_e32 v225, 0x800, v225
	global_store_short_d16_hi v225, v218, s[18:19]
	global_store_short_d16_hi v225, v220, s[18:19] offset:64
	v_add_u32_e32 v225, 0x2800, v225
	s_waitcnt vmcnt(40)
	global_load_short_d16_hi v176, v226, s[18:19]
	global_load_short_d16_hi v184, v226, s[62:63]
	global_load_short_d16_hi v177, v226, s[18:19] offset:64
	global_load_short_d16_hi v185, v226, s[62:63] offset:64
	v_add_u32_e32 v226, 0x800, v226
	global_load_short_d16_hi v178, v226, s[18:19]
	global_load_short_d16_hi v186, v226, s[62:63]
	global_load_short_d16_hi v179, v226, s[18:19] offset:64
	global_load_short_d16_hi v187, v226, s[62:63] offset:64
	v_add_u32_e32 v226, 0x800, v226
	global_load_short_d16_hi v180, v226, s[18:19]
	global_load_short_d16_hi v188, v226, s[62:63]
	global_load_short_d16_hi v181, v226, s[18:19] offset:64
	global_load_short_d16_hi v189, v226, s[62:63] offset:64
	v_add_u32_e32 v226, 0x800, v226
	global_load_short_d16_hi v182, v226, s[18:19]
	global_load_short_d16_hi v190, v226, s[62:63]
	global_load_short_d16_hi v183, v226, s[18:19] offset:64
	global_load_short_d16_hi v191, v226, s[62:63] offset:64
	v_add_u32_e32 v226, 0x2800, v226
	s_waitcnt vmcnt(48)
	v_fma_f32 v209, v68, v152, v144
	v_fma_f32 v210, v52, v153, v145
	v_fma_f32 v211, v69, v154, v146
	v_fma_f32 v212, v53, v155, v147
	v_fma_f32 v213, v70, v156, v148
	v_fma_f32 v214, v54, v157, v149
	v_fma_f32 v215, v71, v158, v150
	v_fma_f32 v216, v55, v159, v151
	v_cvt_pk_bf16_f32 v221, v209, v211
	v_cvt_pk_bf16_f32 v222, v213, v215
	v_cvt_pk_bf16_f32 v223, v210, v212
	v_cvt_pk_bf16_f32 v224, v214, v216
	global_store_short v225, v221, s[18:19]
	global_store_short v225, v223, s[18:19] offset:64
	v_add_u32_e32 v225, 0x800, v225
	global_store_short_d16_hi v225, v221, s[18:19]
	global_store_short_d16_hi v225, v223, s[18:19] offset:64
	v_add_u32_e32 v225, 0x800, v225
	global_store_short v225, v222, s[18:19]
	global_store_short v225, v224, s[18:19] offset:64
	v_add_u32_e32 v225, 0x800, v225
	global_store_short_d16_hi v225, v222, s[18:19]
	global_store_short_d16_hi v225, v224, s[18:19] offset:64
	v_add_u32_e32 v225, 0x2800, v225
	s_waitcnt vmcnt(40)
	global_load_short_d16_hi v144, v226, s[18:19]
	global_load_short_d16_hi v152, v226, s[62:63]
	global_load_short_d16_hi v145, v226, s[18:19] offset:64
	global_load_short_d16_hi v153, v226, s[62:63] offset:64
	v_add_u32_e32 v226, 0x800, v226
	global_load_short_d16_hi v146, v226, s[18:19]
	global_load_short_d16_hi v154, v226, s[62:63]
	global_load_short_d16_hi v147, v226, s[18:19] offset:64
	global_load_short_d16_hi v155, v226, s[62:63] offset:64
	v_add_u32_e32 v226, 0x800, v226
	global_load_short_d16_hi v148, v226, s[18:19]
	global_load_short_d16_hi v156, v226, s[62:63]
	global_load_short_d16_hi v149, v226, s[18:19] offset:64
	global_load_short_d16_hi v157, v226, s[62:63] offset:64
	v_add_u32_e32 v226, 0x800, v226
	global_load_short_d16_hi v150, v226, s[18:19]
	global_load_short_d16_hi v158, v226, s[62:63]
	global_load_short_d16_hi v151, v226, s[18:19] offset:64
	global_load_short_d16_hi v159, v226, s[62:63] offset:64
	v_add_u32_e32 v226, 0x2800, v226
	s_waitcnt vmcnt(48)
	v_fma_f32 v209, v72, v168, v160
	v_fma_f32 v210, v56, v169, v161
	v_fma_f32 v211, v73, v170, v162
	v_fma_f32 v212, v57, v171, v163
	v_fma_f32 v213, v74, v172, v164
	v_fma_f32 v214, v58, v173, v165
	v_fma_f32 v215, v75, v174, v166
	v_fma_f32 v216, v59, v175, v167
	v_cvt_pk_bf16_f32 v217, v209, v211
	v_cvt_pk_bf16_f32 v218, v213, v215
	v_cvt_pk_bf16_f32 v219, v210, v212
	v_cvt_pk_bf16_f32 v220, v214, v216
	global_store_short v225, v217, s[18:19]
	global_store_short v225, v219, s[18:19] offset:64
	v_add_u32_e32 v225, 0x800, v225
	global_store_short_d16_hi v225, v217, s[18:19]
	global_store_short_d16_hi v225, v219, s[18:19] offset:64
	v_add_u32_e32 v225, 0x800, v225
	global_store_short v225, v218, s[18:19]
	global_store_short v225, v220, s[18:19] offset:64
	v_add_u32_e32 v225, 0x800, v225
	global_store_short_d16_hi v225, v218, s[18:19]
	global_store_short_d16_hi v225, v220, s[18:19] offset:64
	v_add_u32_e32 v225, 0x2800, v225
	s_waitcnt vmcnt(40)
	global_load_short_d16_hi v160, v226, s[18:19]
	global_load_short_d16_hi v168, v226, s[62:63]
	global_load_short_d16_hi v161, v226, s[18:19] offset:64
	global_load_short_d16_hi v169, v226, s[62:63] offset:64
	v_add_u32_e32 v226, 0x800, v226
	global_load_short_d16_hi v162, v226, s[18:19]
	global_load_short_d16_hi v170, v226, s[62:63]
	global_load_short_d16_hi v163, v226, s[18:19] offset:64
	global_load_short_d16_hi v171, v226, s[62:63] offset:64
	v_add_u32_e32 v226, 0x800, v226
	global_load_short_d16_hi v164, v226, s[18:19]
	global_load_short_d16_hi v172, v226, s[62:63]
	global_load_short_d16_hi v165, v226, s[18:19] offset:64
	global_load_short_d16_hi v173, v226, s[62:63] offset:64
	v_add_u32_e32 v226, 0x800, v226
	global_load_short_d16_hi v166, v226, s[18:19]
	global_load_short_d16_hi v174, v226, s[62:63]
	global_load_short_d16_hi v167, v226, s[18:19] offset:64
	global_load_short_d16_hi v175, v226, s[62:63] offset:64
	v_add_u32_e32 v226, 0x2800, v226
	s_waitcnt vmcnt(48)
	v_fma_f32 v209, v76, v184, v176
	v_fma_f32 v210, v60, v185, v177
	v_fma_f32 v211, v77, v186, v178
	v_fma_f32 v212, v61, v187, v179
	v_fma_f32 v213, v78, v188, v180
	v_fma_f32 v214, v62, v189, v181
	v_fma_f32 v215, v79, v190, v182
	v_fma_f32 v216, v63, v191, v183
	v_cvt_pk_bf16_f32 v221, v209, v211
	v_cvt_pk_bf16_f32 v222, v213, v215
	v_cvt_pk_bf16_f32 v223, v210, v212
	v_cvt_pk_bf16_f32 v224, v214, v216
	global_store_short v225, v221, s[18:19]
	global_store_short v225, v223, s[18:19] offset:64
	v_add_u32_e32 v225, 0x800, v225
	global_store_short_d16_hi v225, v221, s[18:19]
	global_store_short_d16_hi v225, v223, s[18:19] offset:64
	v_add_u32_e32 v225, 0x800, v225
	global_store_short v225, v222, s[18:19]
	global_store_short v225, v224, s[18:19] offset:64
	v_add_u32_e32 v225, 0x800, v225
	global_store_short_d16_hi v225, v222, s[18:19]
	global_store_short_d16_hi v225, v224, s[18:19] offset:64
	v_add_u32_e32 v225, 0x2800, v225
	s_waitcnt vmcnt(40)
	global_load_short_d16_hi v176, v226, s[18:19]
	global_load_short_d16_hi v184, v226, s[62:63]
	global_load_short_d16_hi v177, v226, s[18:19] offset:64
	global_load_short_d16_hi v185, v226, s[62:63] offset:64
	v_add_u32_e32 v226, 0x800, v226
	global_load_short_d16_hi v178, v226, s[18:19]
	global_load_short_d16_hi v186, v226, s[62:63]
	global_load_short_d16_hi v179, v226, s[18:19] offset:64
	global_load_short_d16_hi v187, v226, s[62:63] offset:64
	v_add_u32_e32 v226, 0x800, v226
	global_load_short_d16_hi v180, v226, s[18:19]
	global_load_short_d16_hi v188, v226, s[62:63]
	global_load_short_d16_hi v181, v226, s[18:19] offset:64
	global_load_short_d16_hi v189, v226, s[62:63] offset:64
	v_add_u32_e32 v226, 0x800, v226
	global_load_short_d16_hi v182, v226, s[18:19]
	global_load_short_d16_hi v190, v226, s[62:63]
	global_load_short_d16_hi v183, v226, s[18:19] offset:64
	global_load_short_d16_hi v191, v226, s[62:63] offset:64
	v_add_u32_e32 v226, 0x2800, v226
	s_waitcnt vmcnt(48)
	v_fma_f32 v209, v32, v152, v144
	v_fma_f32 v210, v16, v153, v145
	v_fma_f32 v211, v33, v154, v146
	v_fma_f32 v212, v17, v155, v147
	v_fma_f32 v213, v34, v156, v148
	v_fma_f32 v214, v18, v157, v149
	v_fma_f32 v215, v35, v158, v150
	v_fma_f32 v216, v19, v159, v151
	v_cvt_pk_bf16_f32 v217, v209, v211
	v_cvt_pk_bf16_f32 v218, v213, v215
	v_cvt_pk_bf16_f32 v219, v210, v212
	v_cvt_pk_bf16_f32 v220, v214, v216
	global_store_short v225, v217, s[18:19]
	global_store_short v225, v219, s[18:19] offset:64
	v_add_u32_e32 v225, 0x800, v225
	global_store_short_d16_hi v225, v217, s[18:19]
	global_store_short_d16_hi v225, v219, s[18:19] offset:64
	v_add_u32_e32 v225, 0x800, v225
	global_store_short v225, v218, s[18:19]
	global_store_short v225, v220, s[18:19] offset:64
	v_add_u32_e32 v225, 0x800, v225
	global_store_short_d16_hi v225, v218, s[18:19]
	global_store_short_d16_hi v225, v220, s[18:19] offset:64
	v_add_u32_e32 v225, 0x2800, v225
	s_waitcnt vmcnt(40)
	global_load_short_d16_hi v144, v226, s[18:19]
	global_load_short_d16_hi v152, v226, s[62:63]
	global_load_short_d16_hi v145, v226, s[18:19] offset:64
	global_load_short_d16_hi v153, v226, s[62:63] offset:64
	v_add_u32_e32 v226, 0x800, v226
	global_load_short_d16_hi v146, v226, s[18:19]
	global_load_short_d16_hi v154, v226, s[62:63]
	global_load_short_d16_hi v147, v226, s[18:19] offset:64
	global_load_short_d16_hi v155, v226, s[62:63] offset:64
	v_add_u32_e32 v226, 0x800, v226
	global_load_short_d16_hi v148, v226, s[18:19]
	global_load_short_d16_hi v156, v226, s[62:63]
	global_load_short_d16_hi v149, v226, s[18:19] offset:64
	global_load_short_d16_hi v157, v226, s[62:63] offset:64
	v_add_u32_e32 v226, 0x800, v226
	global_load_short_d16_hi v150, v226, s[18:19]
	global_load_short_d16_hi v158, v226, s[62:63]
	global_load_short_d16_hi v151, v226, s[18:19] offset:64
	global_load_short_d16_hi v159, v226, s[62:63] offset:64
	s_waitcnt vmcnt(48)
	v_fma_f32 v209, v36, v168, v160
	v_fma_f32 v210, v20, v169, v161
	v_fma_f32 v211, v37, v170, v162
	v_fma_f32 v212, v21, v171, v163
	v_fma_f32 v213, v38, v172, v164
	v_fma_f32 v214, v22, v173, v165
	v_fma_f32 v215, v39, v174, v166
	v_fma_f32 v216, v23, v175, v167
	v_cvt_pk_bf16_f32 v221, v209, v211
	v_cvt_pk_bf16_f32 v222, v213, v215
	v_cvt_pk_bf16_f32 v223, v210, v212
	v_cvt_pk_bf16_f32 v224, v214, v216
	global_store_short v225, v221, s[18:19]
	global_store_short v225, v223, s[18:19] offset:64
	v_add_u32_e32 v225, 0x800, v225
	global_store_short_d16_hi v225, v221, s[18:19]
	global_store_short_d16_hi v225, v223, s[18:19] offset:64
	v_add_u32_e32 v225, 0x800, v225
	global_store_short v225, v222, s[18:19]
	global_store_short v225, v224, s[18:19] offset:64
	v_add_u32_e32 v225, 0x800, v225
	global_store_short_d16_hi v225, v222, s[18:19]
	global_store_short_d16_hi v225, v224, s[18:19] offset:64
	v_add_u32_e32 v225, 0x2800, v225
	s_waitcnt vmcnt(32)
	v_fma_f32 v209, v40, v184, v176
	v_fma_f32 v210, v24, v185, v177
	v_fma_f32 v211, v41, v186, v178
	v_fma_f32 v212, v25, v187, v179
	v_fma_f32 v213, v42, v188, v180
	v_fma_f32 v214, v26, v189, v181
	v_fma_f32 v215, v43, v190, v182
	v_fma_f32 v216, v27, v191, v183
	v_cvt_pk_bf16_f32 v217, v209, v211
	v_cvt_pk_bf16_f32 v218, v213, v215
	v_cvt_pk_bf16_f32 v219, v210, v212
	v_cvt_pk_bf16_f32 v220, v214, v216
	global_store_short v225, v217, s[18:19]
	global_store_short v225, v219, s[18:19] offset:64
	v_add_u32_e32 v225, 0x800, v225
	global_store_short_d16_hi v225, v217, s[18:19]
	global_store_short_d16_hi v225, v219, s[18:19] offset:64
	v_add_u32_e32 v225, 0x800, v225
	global_store_short v225, v218, s[18:19]
	global_store_short v225, v220, s[18:19] offset:64
	v_add_u32_e32 v225, 0x800, v225
	global_store_short_d16_hi v225, v218, s[18:19]
	global_store_short_d16_hi v225, v220, s[18:19] offset:64
	v_add_u32_e32 v225, 0x2800, v225
	s_waitcnt vmcnt(16)
	v_fma_f32 v209, v44, v152, v144
	v_fma_f32 v210, v28, v153, v145
	v_fma_f32 v211, v45, v154, v146
	v_fma_f32 v212, v29, v155, v147
	v_fma_f32 v213, v46, v156, v148
	v_fma_f32 v214, v30, v157, v149
	v_fma_f32 v215, v47, v158, v150
	v_fma_f32 v216, v31, v159, v151
	v_cvt_pk_bf16_f32 v221, v209, v211
	v_cvt_pk_bf16_f32 v222, v213, v215
	v_cvt_pk_bf16_f32 v223, v210, v212
	v_cvt_pk_bf16_f32 v224, v214, v216
	global_store_short v225, v221, s[18:19]
	global_store_short v225, v223, s[18:19] offset:64
	v_add_u32_e32 v225, 0x800, v225
	global_store_short_d16_hi v225, v221, s[18:19]
	global_store_short_d16_hi v225, v223, s[18:19] offset:64
	v_add_u32_e32 v225, 0x800, v225
	global_store_short v225, v222, s[18:19]
	global_store_short v225, v224, s[18:19] offset:64
	v_add_u32_e32 v225, 0x800, v225
	global_store_short_d16_hi v225, v222, s[18:19]
	global_store_short_d16_hi v225, v224, s[18:19] offset:64

.LBB0_3396:
	s_lshl_b64 s[14:15], s[0:1], 9
	s_lshl_b64 s[4:5], s[6:7], 9
	s_waitcnt vmcnt(0)
	s_cmpk_lt_i32 s0, 0x4000
	s_cbranch_scc1 .Lp6y_e3_f
	v_readfirstlane_b32 s64, v208
	s_bitcmp1_b32 s64, 8
	s_cbranch_scc1 .Lp6y_e3_e
.Lp6y_e3_f:
	v_mov_b32_e32 v144, 0
	v_mov_b32_e32 v145, 0
	v_mov_b32_e32 v146, 0
	v_mov_b32_e32 v147, 0
	v_mov_b32_e32 v148, 0
	v_mov_b32_e32 v149, 0
	v_mov_b32_e32 v150, 0
	v_mov_b32_e32 v151, 0
	v_mov_b32_e32 v152, 0
	v_mov_b32_e32 v153, 0
	v_mov_b32_e32 v154, 0
	v_mov_b32_e32 v155, 0
	v_mov_b32_e32 v156, 0
	v_mov_b32_e32 v157, 0
	v_mov_b32_e32 v158, 0
	v_mov_b32_e32 v159, 0
	v_mov_b32_e32 v160, 0
	v_mov_b32_e32 v161, 0
	v_mov_b32_e32 v162, 0
	v_mov_b32_e32 v163, 0
	v_mov_b32_e32 v164, 0
	v_mov_b32_e32 v165, 0
	v_mov_b32_e32 v166, 0
	v_mov_b32_e32 v167, 0
	v_mov_b32_e32 v168, 0
	v_mov_b32_e32 v169, 0
	v_mov_b32_e32 v170, 0
	v_mov_b32_e32 v171, 0
	v_mov_b32_e32 v172, 0
	v_mov_b32_e32 v173, 0
	v_mov_b32_e32 v174, 0
	v_mov_b32_e32 v175, 0
	v_lshrrev_b32_e32 v229, 3, v208
	v_and_b32_e32 v229, 4, v229
	v_lshrrev_b32_e32 v227, 1, v208
	v_and_b32_e32 v227, 0x80, v227
	v_or_b32_e32 v227, v227, v229
	v_and_b32_e32 v228, 0xdf, v208
	v_or_b32_e32 v228, s6, v228
	v_add_u32_e32 v229, s0, v227
	v_lshlrev_b32_e32 v229, 11, v229
	v_lshl_add_u32 v225, v228, 1, v229
	v_mov_b32_e32 v226, v225
	global_load_short_d16_hi v144, v226, s[18:19]
	global_load_short_d16_hi v145, v226, s[18:19] offset:64
	v_add_u32_e32 v226, 0x800, v226
	global_load_short_d16_hi v146, v226, s[18:19]
	global_load_short_d16_hi v147, v226, s[18:19] offset:64
	v_add_u32_e32 v226, 0x800, v226
	global_load_short_d16_hi v148, v226, s[18:19]
	global_load_short_d16_hi v149, v226, s[18:19] offset:64
	v_add_u32_e32 v226, 0x800, v226
	global_load_short_d16_hi v150, v226, s[18:19]
	global_load_short_d16_hi v151, v226, s[18:19] offset:64
	v_add_u32_e32 v226, 0x2800, v226
	global_load_short_d16_hi v152, v226, s[18:19]
	global_load_short_d16_hi v153, v226, s[18:19] offset:64
	v_add_u32_e32 v226, 0x800, v226
	global_load_short_d16_hi v154, v226, s[18:19]
	global_load_short_d16_hi v155, v226, s[18:19] offset:64
	v_add_u32_e32 v226, 0x800, v226
	global_load_short_d16_hi v156, v226, s[18:19]
	global_load_short_d16_hi v157, v226, s[18:19] offset:64
	v_add_u32_e32 v226, 0x800, v226
	global_load_short_d16_hi v158, v226, s[18:19]
	global_load_short_d16_hi v159, v226, s[18:19] offset:64
	v_add_u32_e32 v226, 0x2800, v226
	global_load_short_d16_hi v160, v226, s[18:19]
	global_load_short_d16_hi v161, v226, s[18:19] offset:64
	v_add_u32_e32 v226, 0x800, v226
	global_load_short_d16_hi v162, v226, s[18:19]
	global_load_short_d16_hi v163, v226, s[18:19] offset:64
	v_add_u32_e32 v226, 0x800, v226
	global_load_short_d16_hi v164, v226, s[18:19]
	global_load_short_d16_hi v165, v226, s[18:19] offset:64
	v_add_u32_e32 v226, 0x800, v226
	global_load_short_d16_hi v166, v226, s[18:19]
	global_load_short_d16_hi v167, v226, s[18:19] offset:64
	v_add_u32_e32 v226, 0x2800, v226
	global_load_short_d16_hi v168, v226, s[18:19]
	global_load_short_d16_hi v169, v226, s[18:19] offset:64
	v_add_u32_e32 v226, 0x800, v226
	global_load_short_d16_hi v170, v226, s[18:19]
	global_load_short_d16_hi v171, v226, s[18:19] offset:64
	v_add_u32_e32 v226, 0x800, v226
	global_load_short_d16_hi v172, v226, s[18:19]
	global_load_short_d16_hi v173, v226, s[18:19] offset:64
	v_add_u32_e32 v226, 0x800, v226
	global_load_short_d16_hi v174, v226, s[18:19]
	global_load_short_d16_hi v175, v226, s[18:19] offset:64
	v_add_u32_e32 v226, 0x2800, v226
	s_waitcnt vmcnt(24)
	v_mul_f32_e32 v209, v128, v144
	v_mul_f32_e32 v210, v112, v145
	v_mul_f32_e32 v211, v129, v146
	v_mul_f32_e32 v212, v113, v147
	v_mul_f32_e32 v213, v130, v148
	v_mul_f32_e32 v214, v114, v149
	v_mul_f32_e32 v215, v131, v150
	v_mul_f32_e32 v216, v115, v151
	v_cvt_pk_bf16_f32 v217, v209, v211
	v_cvt_pk_bf16_f32 v218, v213, v215
	v_cvt_pk_bf16_f32 v219, v210, v212
	v_cvt_pk_bf16_f32 v220, v214, v216
	global_store_short v225, v217, s[18:19]
	global_store_short v225, v219, s[18:19] offset:64
	v_add_u32_e32 v225, 0x800, v225
	global_store_short_d16_hi v225, v217, s[18:19]
	global_store_short_d16_hi v225, v219, s[18:19] offset:64
	v_add_u32_e32 v225, 0x800, v225
	global_store_short v225, v218, s[18:19]
	global_store_short v225, v220, s[18:19] offset:64
	v_add_u32_e32 v225, 0x800, v225
	global_store_short_d16_hi v225, v218, s[18:19]
	global_store_short_d16_hi v225, v220, s[18:19] offset:64
	v_add_u32_e32 v225, 0x2800, v225
	global_load_short_d16_hi v144, v226, s[18:19]
	global_load_short_d16_hi v145, v226, s[18:19] offset:64
	v_add_u32_e32 v226, 0x800, v226
	global_load_short_d16_hi v146, v226, s[18:19]
	global_load_short_d16_hi v147, v226, s[18:19] offset:64
	v_add_u32_e32 v226, 0x800, v226
	global_load_short_d16_hi v148, v226, s[18:19]
	global_load_short_d16_hi v149, v226, s[18:19] offset:64
	v_add_u32_e32 v226, 0x800, v226
	global_load_short_d16_hi v150, v226, s[18:19]
	global_load_short_d16_hi v151, v226, s[18:19] offset:64
	v_add_u32_e32 v226, 0x2800, v226
	s_waitcnt vmcnt(32)
	v_mul_f32_e32 v209, v132, v152
	v_mul_f32_e32 v210, v116, v153
	v_mul_f32_e32 v211, v133, v154
	v_mul_f32_e32 v212, v117, v155
	v_mul_f32_e32 v213, v134, v156
	v_mul_f32_e32 v214, v118, v157
	v_mul_f32_e32 v215, v135, v158
	v_mul_f32_e32 v216, v119, v159
	v_cvt_pk_bf16_f32 v221, v209, v211
	v_cvt_pk_bf16_f32 v222, v213, v215
	v_cvt_pk_bf16_f32 v223, v210, v212
	v_cvt_pk_bf16_f32 v224, v214, v216
	global_store_short v225, v221, s[18:19]
	global_store_short v225, v223, s[18:19] offset:64
	v_add_u32_e32 v225, 0x800, v225
	global_store_short_d16_hi v225, v221, s[18:19]
	global_store_short_d16_hi v225, v223, s[18:19] offset:64
	v_add_u32_e32 v225, 0x800, v225
	global_store_short v225, v222, s[18:19]
	global_store_short v225, v224, s[18:19] offset:64
	v_add_u32_e32 v225, 0x800, v225
	global_store_short_d16_hi v225, v222, s[18:19]
	global_store_short_d16_hi v225, v224, s[18:19] offset:64
	v_add_u32_e32 v225, 0x2800, v225
	global_load_short_d16_hi v152, v226, s[18:19]
	global_load_short_d16_hi v153, v226, s[18:19] offset:64
	v_add_u32_e32 v226, 0x800, v226
	global_load_short_d16_hi v154, v226, s[18:19]
	global_load_short_d16_hi v155, v226, s[18:19] offset:64
	v_add_u32_e32 v226, 0x800, v226
	global_load_short_d16_hi v156, v226, s[18:19]
	global_load_short_d16_hi v157, v226, s[18:19] offset:64
	v_add_u32_e32 v226, 0x800, v226
	global_load_short_d16_hi v158, v226, s[18:19]
	global_load_short_d16_hi v159, v226, s[18:19] offset:64
	v_add_u32_e32 v226, 0x2800, v226
	s_waitcnt vmcnt(40)
	v_mul_f32_e32 v209, v136, v160
	v_mul_f32_e32 v210, v120, v161
	v_mul_f32_e32 v211, v137, v162
	v_mul_f32_e32 v212, v121, v163
	v_mul_f32_e32 v213, v138, v164
	v_mul_f32_e32 v214, v122, v165
	v_mul_f32_e32 v215, v139, v166
	v_mul_f32_e32 v216, v123, v167
	v_cvt_pk_bf16_f32 v217, v209, v211
	v_cvt_pk_bf16_f32 v218, v213, v215
	v_cvt_pk_bf16_f32 v219, v210, v212
	v_cvt_pk_bf16_f32 v220, v214, v216
	global_store_short v225, v217, s[18:19]
	global_store_short v225, v219, s[18:19] offset:64
	v_add_u32_e32 v225, 0x800, v225
	global_store_short_d16_hi v225, v217, s[18:19]
	global_store_short_d16_hi v225, v219, s[18:19] offset:64
	v_add_u32_e32 v225, 0x800, v225
	global_store_short v225, v218, s[18:19]
	global_store_short v225, v220, s[18:19] offset:64
	v_add_u32_e32 v225, 0x800, v225
	global_store_short_d16_hi v225, v218, s[18:19]
	global_store_short_d16_hi v225, v220, s[18:19] offset:64
	v_add_u32_e32 v225, 0x2800, v225
	global_load_short_d16_hi v160, v226, s[18:19]
	global_load_short_d16_hi v161, v226, s[18:19] offset:64
	v_add_u32_e32 v226, 0x800, v226
	global_load_short_d16_hi v162, v226, s[18:19]
	global_load_short_d16_hi v163, v226, s[18:19] offset:64
	v_add_u32_e32 v226, 0x800, v226
	global_load_short_d16_hi v164, v226, s[18:19]
	global_load_short_d16_hi v165, v226, s[18:19] offset:64
	v_add_u32_e32 v226, 0x800, v226
	global_load_short_d16_hi v166, v226, s[18:19]
	global_load_short_d16_hi v167, v226, s[18:19] offset:64
	v_add_u32_e32 v226, 0x2800, v226
	s_waitcnt vmcnt(48)
	v_mul_f32_e32 v209, v140, v168
	v_mul_f32_e32 v210, v124, v169
	v_mul_f32_e32 v211, v141, v170
	v_mul_f32_e32 v212, v125, v171
	v_mul_f32_e32 v213, v142, v172
	v_mul_f32_e32 v214, v126, v173
	v_mul_f32_e32 v215, v143, v174
	v_mul_f32_e32 v216, v127, v175
	v_cvt_pk_bf16_f32 v221, v209, v211
	v_cvt_pk_bf16_f32 v222, v213, v215
	v_cvt_pk_bf16_f32 v223, v210, v212
	v_cvt_pk_bf16_f32 v224, v214, v216
	global_store_short v225, v221, s[18:19]
	global_store_short v225, v223, s[18:19] offset:64
	v_add_u32_e32 v225, 0x800, v225
	global_store_short_d16_hi v225, v221, s[18:19]
	global_store_short_d16_hi v225, v223, s[18:19] offset:64
	v_add_u32_e32 v225, 0x800, v225
	global_store_short v225, v222, s[18:19]
	global_store_short v225, v224, s[18:19] offset:64
	v_add_u32_e32 v225, 0x800, v225
	global_store_short_d16_hi v225, v222, s[18:19]
	global_store_short_d16_hi v225, v224, s[18:19] offset:64
	v_add_u32_e32 v225, 0x2800, v225
	s_waitcnt vmcnt(40)
	global_load_short_d16_hi v168, v226, s[18:19]
	global_load_short_d16_hi v169, v226, s[18:19] offset:64
	v_add_u32_e32 v226, 0x800, v226
	global_load_short_d16_hi v170, v226, s[18:19]
	global_load_short_d16_hi v171, v226, s[18:19] offset:64
	v_add_u32_e32 v226, 0x800, v226
	global_load_short_d16_hi v172, v226, s[18:19]
	global_load_short_d16_hi v173, v226, s[18:19] offset:64
	v_add_u32_e32 v226, 0x800, v226
	global_load_short_d16_hi v174, v226, s[18:19]
	global_load_short_d16_hi v175, v226, s[18:19] offset:64
	v_add_u32_e32 v226, 0x2800, v226
	v_mul_f32_e32 v209, v80, v144
	v_mul_f32_e32 v210, v48, v145
	v_mul_f32_e32 v211, v81, v146
	v_mul_f32_e32 v212, v49, v147
	v_mul_f32_e32 v213, v82, v148
	v_mul_f32_e32 v214, v50, v149
	v_mul_f32_e32 v215, v83, v150
	v_mul_f32_e32 v216, v51, v151
	v_cvt_pk_bf16_f32 v217, v209, v211
	v_cvt_pk_bf16_f32 v218, v213, v215
	v_cvt_pk_bf16_f32 v219, v210, v212
	v_cvt_pk_bf16_f32 v220, v214, v216
	global_store_short v225, v217, s[18:19]
	global_store_short v225, v219, s[18:19] offset:64
	v_add_u32_e32 v225, 0x800, v225
	global_store_short_d16_hi v225, v217, s[18:19]
	global_store_short_d16_hi v225, v219, s[18:19] offset:64
	v_add_u32_e32 v225, 0x800, v225
	global_store_short v225, v218, s[18:19]
	global_store_short v225, v220, s[18:19] offset:64
	v_add_u32_e32 v225, 0x800, v225
	global_store_short_d16_hi v225, v218, s[18:19]
	global_store_short_d16_hi v225, v220, s[18:19] offset:64
	v_add_u32_e32 v225, 0x2800, v225
	s_waitcnt vmcnt(40)
	global_load_short_d16_hi v144, v226, s[18:19]
	global_load_short_d16_hi v145, v226, s[18:19] offset:64
	v_add_u32_e32 v226, 0x800, v226
	global_load_short_d16_hi v146, v226, s[18:19]
	global_load_short_d16_hi v147, v226, s[18:19] offset:64
	v_add_u32_e32 v226, 0x800, v226
	global_load_short_d16_hi v148, v226, s[18:19]
	global_load_short_d16_hi v149, v226, s[18:19] offset:64
	v_add_u32_e32 v226, 0x800, v226
	global_load_short_d16_hi v150, v226, s[18:19]
	global_load_short_d16_hi v151, v226, s[18:19] offset:64
	v_add_u32_e32 v226, 0x2800, v226
	v_mul_f32_e32 v209, v84, v152
	v_mul_f32_e32 v210, v52, v153
	v_mul_f32_e32 v211, v85, v154
	v_mul_f32_e32 v212, v53, v155
	v_mul_f32_e32 v213, v86, v156
	v_mul_f32_e32 v214, v54, v157
	v_mul_f32_e32 v215, v87, v158
	v_mul_f32_e32 v216, v55, v159
	v_cvt_pk_bf16_f32 v221, v209, v211
	v_cvt_pk_bf16_f32 v222, v213, v215
	v_cvt_pk_bf16_f32 v223, v210, v212
	v_cvt_pk_bf16_f32 v224, v214, v216
	global_store_short v225, v221, s[18:19]
	global_store_short v225, v223, s[18:19] offset:64
	v_add_u32_e32 v225, 0x800, v225
	global_store_short_d16_hi v225, v221, s[18:19]
	global_store_short_d16_hi v225, v223, s[18:19] offset:64
	v_add_u32_e32 v225, 0x800, v225
	global_store_short v225, v222, s[18:19]
	global_store_short v225, v224, s[18:19] offset:64
	v_add_u32_e32 v225, 0x800, v225
	global_store_short_d16_hi v225, v222, s[18:19]
	global_store_short_d16_hi v225, v224, s[18:19] offset:64
	v_add_u32_e32 v225, 0x2800, v225
	s_waitcnt vmcnt(40)
	global_load_short_d16_hi v152, v226, s[18:19]
	global_load_short_d16_hi v153, v226, s[18:19] offset:64
	v_add_u32_e32 v226, 0x800, v226
	global_load_short_d16_hi v154, v226, s[18:19]
	global_load_short_d16_hi v155, v226, s[18:19] offset:64
	v_add_u32_e32 v226, 0x800, v226
	global_load_short_d16_hi v156, v226, s[18:19]
	global_load_short_d16_hi v157, v226, s[18:19] offset:64
	v_add_u32_e32 v226, 0x800, v226
	global_load_short_d16_hi v158, v226, s[18:19]
	global_load_short_d16_hi v159, v226, s[18:19] offset:64
	v_add_u32_e32 v226, 0x2800, v226
	v_mul_f32_e32 v209, v88, v160
	v_mul_f32_e32 v210, v56, v161
	v_mul_f32_e32 v211, v89, v162
	v_mul_f32_e32 v212, v57, v163
	v_mul_f32_e32 v213, v90, v164
	v_mul_f32_e32 v214, v58, v165
	v_mul_f32_e32 v215, v91, v166
	v_mul_f32_e32 v216, v59, v167
	v_cvt_pk_bf16_f32 v217, v209, v211
	v_cvt_pk_bf16_f32 v218, v213, v215
	v_cvt_pk_bf16_f32 v219, v210, v212
	v_cvt_pk_bf16_f32 v220, v214, v216
	global_store_short v225, v217, s[18:19]
	global_store_short v225, v219, s[18:19] offset:64
	v_add_u32_e32 v225, 0x800, v225
	global_store_short_d16_hi v225, v217, s[18:19]
	global_store_short_d16_hi v225, v219, s[18:19] offset:64
	v_add_u32_e32 v225, 0x800, v225
	global_store_short v225, v218, s[18:19]
	global_store_short v225, v220, s[18:19] offset:64
	v_add_u32_e32 v225, 0x800, v225
	global_store_short_d16_hi v225, v218, s[18:19]
	global_store_short_d16_hi v225, v220, s[18:19] offset:64
	v_add_u32_e32 v225, 0x2800, v225
	s_waitcnt vmcnt(40)
	global_load_short_d16_hi v160, v226, s[18:19]
	global_load_short_d16_hi v161, v226, s[18:19] offset:64
	v_add_u32_e32 v226, 0x800, v226
	global_load_short_d16_hi v162, v226, s[18:19]
	global_load_short_d16_hi v163, v226, s[18:19] offset:64
	v_add_u32_e32 v226, 0x800, v226
	global_load_short_d16_hi v164, v226, s[18:19]
	global_load_short_d16_hi v165, v226, s[18:19] offset:64
	v_add_u32_e32 v226, 0x800, v226
	global_load_short_d16_hi v166, v226, s[18:19]
	global_load_short_d16_hi v167, v226, s[18:19] offset:64
	v_add_u32_e32 v226, 0x2800, v226
	v_mul_f32_e32 v209, v92, v168
	v_mul_f32_e32 v210, v60, v169
	v_mul_f32_e32 v211, v93, v170
	v_mul_f32_e32 v212, v61, v171
	v_mul_f32_e32 v213, v94, v172
	v_mul_f32_e32 v214, v62, v173
	v_mul_f32_e32 v215, v95, v174
	v_mul_f32_e32 v216, v63, v175
	v_cvt_pk_bf16_f32 v221, v209, v211
	v_cvt_pk_bf16_f32 v222, v213, v215
	v_cvt_pk_bf16_f32 v223, v210, v212
	v_cvt_pk_bf16_f32 v224, v214, v216
	global_store_short v225, v221, s[18:19]
	global_store_short v225, v223, s[18:19] offset:64
	v_add_u32_e32 v225, 0x800, v225
	global_store_short_d16_hi v225, v221, s[18:19]
	global_store_short_d16_hi v225, v223, s[18:19] offset:64
	v_add_u32_e32 v225, 0x800, v225
	global_store_short v225, v222, s[18:19]
	global_store_short v225, v224, s[18:19] offset:64
	v_add_u32_e32 v225, 0x800, v225
	global_store_short_d16_hi v225, v222, s[18:19]
	global_store_short_d16_hi v225, v224, s[18:19] offset:64
	v_add_u32_e32 v225, 0x2800, v225
	s_cmpk_lt_i32 s0, 0x4000
	s_cbranch_scc1 .Lp6y_e3_c
	s_waitcnt vmcnt(0)
	s_branch .Lp6y_e3_e
.Lp6y_e3_c:
	s_waitcnt vmcnt(40)
	global_load_short_d16_hi v168, v226, s[18:19]
	global_load_short_d16_hi v169, v226, s[18:19] offset:64
	v_add_u32_e32 v226, 0x800, v226
	global_load_short_d16_hi v170, v226, s[18:19]
	global_load_short_d16_hi v171, v226, s[18:19] offset:64
	v_add_u32_e32 v226, 0x800, v226
	global_load_short_d16_hi v172, v226, s[18:19]
	global_load_short_d16_hi v173, v226, s[18:19] offset:64
	v_add_u32_e32 v226, 0x800, v226
	global_load_short_d16_hi v174, v226, s[18:19]
	global_load_short_d16_hi v175, v226, s[18:19] offset:64
	v_add_u32_e32 v226, 0x2800, v226
	v_mul_f32_e32 v209, v96, v144
	v_mul_f32_e32 v210, v64, v145
	v_mul_f32_e32 v211, v97, v146
	v_mul_f32_e32 v212, v65, v147
	v_mul_f32_e32 v213, v98, v148
	v_mul_f32_e32 v214, v66, v149
	v_mul_f32_e32 v215, v99, v150
	v_mul_f32_e32 v216, v67, v151
	v_cvt_pk_bf16_f32 v217, v209, v211
	v_cvt_pk_bf16_f32 v218, v213, v215
	v_cvt_pk_bf16_f32 v219, v210, v212
	v_cvt_pk_bf16_f32 v220, v214, v216
	global_store_short v225, v217, s[18:19]
	global_store_short v225, v219, s[18:19] offset:64
	v_add_u32_e32 v225, 0x800, v225
	global_store_short_d16_hi v225, v217, s[18:19]
	global_store_short_d16_hi v225, v219, s[18:19] offset:64
	v_add_u32_e32 v225, 0x800, v225
	global_store_short v225, v218, s[18:19]
	global_store_short v225, v220, s[18:19] offset:64
	v_add_u32_e32 v225, 0x800, v225
	global_store_short_d16_hi v225, v218, s[18:19]
	global_store_short_d16_hi v225, v220, s[18:19] offset:64
	v_add_u32_e32 v225, 0x2800, v225
	s_waitcnt vmcnt(40)
	global_load_short_d16_hi v144, v226, s[18:19]
	global_load_short_d16_hi v145, v226, s[18:19] offset:64
	v_add_u32_e32 v226, 0x800, v226
	global_load_short_d16_hi v146, v226, s[18:19]
	global_load_short_d16_hi v147, v226, s[18:19] offset:64
	v_add_u32_e32 v226, 0x800, v226
	global_load_short_d16_hi v148, v226, s[18:19]
	global_load_short_d16_hi v149, v226, s[18:19] offset:64
	v_add_u32_e32 v226, 0x800, v226
	global_load_short_d16_hi v150, v226, s[18:19]
	global_load_short_d16_hi v151, v226, s[18:19] offset:64
	v_add_u32_e32 v226, 0x2800, v226
	v_mul_f32_e32 v209, v100, v152
	v_mul_f32_e32 v210, v68, v153
	v_mul_f32_e32 v211, v101, v154
	v_mul_f32_e32 v212, v69, v155
	v_mul_f32_e32 v213, v102, v156
	v_mul_f32_e32 v214, v70, v157
	v_mul_f32_e32 v215, v103, v158
	v_mul_f32_e32 v216, v71, v159
	v_cvt_pk_bf16_f32 v221, v209, v211
	v_cvt_pk_bf16_f32 v222, v213, v215
	v_cvt_pk_bf16_f32 v223, v210, v212
	v_cvt_pk_bf16_f32 v224, v214, v216
	global_store_short v225, v221, s[18:19]
	global_store_short v225, v223, s[18:19] offset:64
	v_add_u32_e32 v225, 0x800, v225
	global_store_short_d16_hi v225, v221, s[18:19]
	global_store_short_d16_hi v225, v223, s[18:19] offset:64
	v_add_u32_e32 v225, 0x800, v225
	global_store_short v225, v222, s[18:19]
	global_store_short v225, v224, s[18:19] offset:64
	v_add_u32_e32 v225, 0x800, v225
	global_store_short_d16_hi v225, v222, s[18:19]
	global_store_short_d16_hi v225, v224, s[18:19] offset:64
	v_add_u32_e32 v225, 0x2800, v225
	s_waitcnt vmcnt(40)
	global_load_short_d16_hi v152, v226, s[18:19]
	global_load_short_d16_hi v153, v226, s[18:19] offset:64
	v_add_u32_e32 v226, 0x800, v226
	global_load_short_d16_hi v154, v226, s[18:19]
	global_load_short_d16_hi v155, v226, s[18:19] offset:64
	v_add_u32_e32 v226, 0x800, v226
	global_load_short_d16_hi v156, v226, s[18:19]
	global_load_short_d16_hi v157, v226, s[18:19] offset:64
	v_add_u32_e32 v226, 0x800, v226
	global_load_short_d16_hi v158, v226, s[18:19]
	global_load_short_d16_hi v159, v226, s[18:19] offset:64
	v_add_u32_e32 v226, 0x2800, v226
	v_mul_f32_e32 v209, v104, v160
	v_mul_f32_e32 v210, v72, v161
	v_mul_f32_e32 v211, v105, v162
	v_mul_f32_e32 v212, v73, v163
	v_mul_f32_e32 v213, v106, v164
	v_mul_f32_e32 v214, v74, v165
	v_mul_f32_e32 v215, v107, v166
	v_mul_f32_e32 v216, v75, v167
	v_cvt_pk_bf16_f32 v217, v209, v211
	v_cvt_pk_bf16_f32 v218, v213, v215
	v_cvt_pk_bf16_f32 v219, v210, v212
	v_cvt_pk_bf16_f32 v220, v214, v216
	global_store_short v225, v217, s[18:19]
	global_store_short v225, v219, s[18:19] offset:64
	v_add_u32_e32 v225, 0x800, v225
	global_store_short_d16_hi v225, v217, s[18:19]
	global_store_short_d16_hi v225, v219, s[18:19] offset:64
	v_add_u32_e32 v225, 0x800, v225
	global_store_short v225, v218, s[18:19]
	global_store_short v225, v220, s[18:19] offset:64
	v_add_u32_e32 v225, 0x800, v225
	global_store_short_d16_hi v225, v218, s[18:19]
	global_store_short_d16_hi v225, v220, s[18:19] offset:64
	v_add_u32_e32 v225, 0x2800, v225
	s_waitcnt vmcnt(40)
	global_load_short_d16_hi v160, v226, s[18:19]
	global_load_short_d16_hi v161, v226, s[18:19] offset:64
	v_add_u32_e32 v226, 0x800, v226
	global_load_short_d16_hi v162, v226, s[18:19]
	global_load_short_d16_hi v163, v226, s[18:19] offset:64
	v_add_u32_e32 v226, 0x800, v226
	global_load_short_d16_hi v164, v226, s[18:19]
	global_load_short_d16_hi v165, v226, s[18:19] offset:64
	v_add_u32_e32 v226, 0x800, v226
	global_load_short_d16_hi v166, v226, s[18:19]
	global_load_short_d16_hi v167, v226, s[18:19] offset:64
	v_add_u32_e32 v226, 0x2800, v226
	v_mul_f32_e32 v209, v108, v168
	v_mul_f32_e32 v210, v76, v169
	v_mul_f32_e32 v211, v109, v170
	v_mul_f32_e32 v212, v77, v171
	v_mul_f32_e32 v213, v110, v172
	v_mul_f32_e32 v214, v78, v173
	v_mul_f32_e32 v215, v111, v174
	v_mul_f32_e32 v216, v79, v175
	v_cvt_pk_bf16_f32 v221, v209, v211
	v_cvt_pk_bf16_f32 v222, v213, v215
	v_cvt_pk_bf16_f32 v223, v210, v212
	v_cvt_pk_bf16_f32 v224, v214, v216
	global_store_short v225, v221, s[18:19]
	global_store_short v225, v223, s[18:19] offset:64
	v_add_u32_e32 v225, 0x800, v225
	global_store_short_d16_hi v225, v221, s[18:19]
	global_store_short_d16_hi v225, v223, s[18:19] offset:64
	v_add_u32_e32 v225, 0x800, v225
	global_store_short v225, v222, s[18:19]
	global_store_short v225, v224, s[18:19] offset:64
	v_add_u32_e32 v225, 0x800, v225
	global_store_short_d16_hi v225, v222, s[18:19]
	global_store_short_d16_hi v225, v224, s[18:19] offset:64
	v_add_u32_e32 v225, 0x2800, v225
	s_waitcnt vmcnt(40)
	global_load_short_d16_hi v168, v226, s[18:19]
	global_load_short_d16_hi v169, v226, s[18:19] offset:64
	v_add_u32_e32 v226, 0x800, v226
	global_load_short_d16_hi v170, v226, s[18:19]
	global_load_short_d16_hi v171, v226, s[18:19] offset:64
	v_add_u32_e32 v226, 0x800, v226
	global_load_short_d16_hi v172, v226, s[18:19]
	global_load_short_d16_hi v173, v226, s[18:19] offset:64
	v_add_u32_e32 v226, 0x800, v226
	global_load_short_d16_hi v174, v226, s[18:19]
	global_load_short_d16_hi v175, v226, s[18:19] offset:64
	v_mul_f32_e32 v209, v32, v144
	v_mul_f32_e32 v210, v16, v145
	v_mul_f32_e32 v211, v33, v146
	v_mul_f32_e32 v212, v17, v147
	v_mul_f32_e32 v213, v34, v148
	v_mul_f32_e32 v214, v18, v149
	v_mul_f32_e32 v215, v35, v150
	v_mul_f32_e32 v216, v19, v151
	v_cvt_pk_bf16_f32 v217, v209, v211
	v_cvt_pk_bf16_f32 v218, v213, v215
	v_cvt_pk_bf16_f32 v219, v210, v212
	v_cvt_pk_bf16_f32 v220, v214, v216
	global_store_short v225, v217, s[18:19]
	global_store_short v225, v219, s[18:19] offset:64
	v_add_u32_e32 v225, 0x800, v225
	global_store_short_d16_hi v225, v217, s[18:19]
	global_store_short_d16_hi v225, v219, s[18:19] offset:64
	v_add_u32_e32 v225, 0x800, v225
	global_store_short v225, v218, s[18:19]
	global_store_short v225, v220, s[18:19] offset:64
	v_add_u32_e32 v225, 0x800, v225
	global_store_short_d16_hi v225, v218, s[18:19]
	global_store_short_d16_hi v225, v220, s[18:19] offset:64
	v_add_u32_e32 v225, 0x2800, v225
	s_waitcnt vmcnt(40)
	v_mul_f32_e32 v209, v36, v152
	v_mul_f32_e32 v210, v20, v153
	v_mul_f32_e32 v211, v37, v154
	v_mul_f32_e32 v212, v21, v155
	v_mul_f32_e32 v213, v38, v156
	v_mul_f32_e32 v214, v22, v157
	v_mul_f32_e32 v215, v39, v158
	v_mul_f32_e32 v216, v23, v159
	v_cvt_pk_bf16_f32 v221, v209, v211
	v_cvt_pk_bf16_f32 v222, v213, v215
	v_cvt_pk_bf16_f32 v223, v210, v212
	v_cvt_pk_bf16_f32 v224, v214, v216
	global_store_short v225, v221, s[18:19]
	global_store_short v225, v223, s[18:19] offset:64
	v_add_u32_e32 v225, 0x800, v225
	global_store_short_d16_hi v225, v221, s[18:19]
	global_store_short_d16_hi v225, v223, s[18:19] offset:64
	v_add_u32_e32 v225, 0x800, v225
	global_store_short v225, v222, s[18:19]
	global_store_short v225, v224, s[18:19] offset:64
	v_add_u32_e32 v225, 0x800, v225
	global_store_short_d16_hi v225, v222, s[18:19]
	global_store_short_d16_hi v225, v224, s[18:19] offset:64
	v_add_u32_e32 v225, 0x2800, v225
	s_waitcnt vmcnt(32)
	v_mul_f32_e32 v209, v40, v160
	v_mul_f32_e32 v210, v24, v161
	v_mul_f32_e32 v211, v41, v162
	v_mul_f32_e32 v212, v25, v163
	v_mul_f32_e32 v213, v42, v164
	v_mul_f32_e32 v214, v26, v165
	v_mul_f32_e32 v215, v43, v166
	v_mul_f32_e32 v216, v27, v167
	v_cvt_pk_bf16_f32 v217, v209, v211
	v_cvt_pk_bf16_f32 v218, v213, v215
	v_cvt_pk_bf16_f32 v219, v210, v212
	v_cvt_pk_bf16_f32 v220, v214, v216
	global_store_short v225, v217, s[18:19]
	global_store_short v225, v219, s[18:19] offset:64
	v_add_u32_e32 v225, 0x800, v225
	global_store_short_d16_hi v225, v217, s[18:19]
	global_store_short_d16_hi v225, v219, s[18:19] offset:64
	v_add_u32_e32 v225, 0x800, v225
	global_store_short v225, v218, s[18:19]
	global_store_short v225, v220, s[18:19] offset:64
	v_add_u32_e32 v225, 0x800, v225
	global_store_short_d16_hi v225, v218, s[18:19]
	global_store_short_d16_hi v225, v220, s[18:19] offset:64
	v_add_u32_e32 v225, 0x2800, v225
	s_waitcnt vmcnt(24)
	v_mul_f32_e32 v209, v44, v168
	v_mul_f32_e32 v210, v28, v169
	v_mul_f32_e32 v211, v45, v170
	v_mul_f32_e32 v212, v29, v171
	v_mul_f32_e32 v213, v46, v172
	v_mul_f32_e32 v214, v30, v173
	v_mul_f32_e32 v215, v47, v174
	v_mul_f32_e32 v216, v31, v175
	v_cvt_pk_bf16_f32 v221, v209, v211
	v_cvt_pk_bf16_f32 v222, v213, v215
	v_cvt_pk_bf16_f32 v223, v210, v212
	v_cvt_pk_bf16_f32 v224, v214, v216
	global_store_short v225, v221, s[18:19]
	global_store_short v225, v223, s[18:19] offset:64
	v_add_u32_e32 v225, 0x800, v225
	global_store_short_d16_hi v225, v221, s[18:19]
	global_store_short_d16_hi v225, v223, s[18:19] offset:64
	v_add_u32_e32 v225, 0x800, v225
	global_store_short v225, v222, s[18:19]
	global_store_short v225, v224, s[18:19] offset:64
	v_add_u32_e32 v225, 0x800, v225
	global_store_short_d16_hi v225, v222, s[18:19]
	global_store_short_d16_hi v225, v224, s[18:19] offset:64
